# FFN-in: 66 units pre-run by idle CUs during the 4-tile tail round of the preceding residual GEMM (phases 10, 26); FFN-in phase then needs 11 rounds instead of 12 (static unit re-assignment, same work
# speedup vs baseline: 1.0095x; 1.0095x over previous
; #define PG8_LAS __attribute__((address_space(3)))
; #define LAS __attribute__((address_space(3)))
; __device__ __forceinline__ unsigned xb_add(unsigned* p, unsigned v) { return __hip_atomic_fetch_add(p, v, __ATOMIC_RELAXED, __HIP_MEMORY_SCOPE_AGENT); }
; __device__ __forceinline__ unsigned xb_xcc_id() { return (unsigned)__builtin_amdgcn_s_getreg((3 << 11) | 20) & 0xFu; }
; __device__ __forceinline__ XcdBarrier xcd_barrier_post(unsigned* bar, volatile LAS unsigned* st) {
;     XcdBarrier b; b.bar = bar; b.x = xb_xcc_id(); b.st = st;
;     if (threadIdx.x == 0) (void)xb_add(&bar[XB_XCNT(b.x)], 1u);
;     return b;
; }
; __device__ __forceinline__ void xcd_barrier_complete(unsigned* bar, unsigned x, unsigned& nloc, unsigned& nx) {
;     const unsigned G = gridDim.x * gridDim.y * gridDim.z;
; __global__ void __launch_bounds__(512, 2) fwd_mega(Args a_) {
;     ArgP ap0 = (ArgP)__builtin_amdgcn_kernarg_segment_ptr();
;     extern __shared__ __attribute__((aligned(16))) unsigned char lds[];
;     cg::grid_group grid = cg::this_grid();
;     PG8_LAS float* edge = (PG8_LAS float*)((PG8_LAS unsigned char*)lds + RING_BYTES);
;     volatile LAS unsigned* bst = (volatile LAS unsigned*)((LAS unsigned char*)lds + LDS_BYTES - 16);
;     const int wave_s = __builtin_amdgcn_readfirstlane(threadIdx.x >> 6);
;     if (threadIdx.x < 4) bst[threadIdx.x] = 0u;
;     __syncthreads();
;     XcdBarrier xbar = xcd_barrier_post((unsigned*)(ap0->ws + WS_BAR), bst);
;     grid.sync();
.LBB0_5:
	s_or_b64 exec, exec, s[6:7]
	v_lshrrev_b32_e32 v2, 20, v0
	v_lshrrev_b32_e32 v0, 10, v0
	v_or_b32_e32 v0, v0, v2
	s_movk_i32 s6, 0x3ff
	v_and_or_b32 v0, v0, s6, v1
	v_cmp_eq_u32_e32 vcc, 0, v0
	s_barrier
	s_and_b32 s84, s3, 0xffffffc0
	s_cmpk_lt_i32 s96, 0x104
	s_cselect_b64 s[6:7], -1, 0
	s_ashr_i32 s97, s96, 31
	s_lshr_b32 s3, s97, 29
	s_add_i32 s3, s96, s3
	s_ashr_i32 s85, s3, 3
	s_and_b32 s3, s3, -8
	s_sub_i32 s86, s96, s3
	s_lshl_b32 s3, s86, 5
	s_or_b32 s3, s3, 4
	s_ashr_i32 s87, s94, 31
	s_lshl_b32 s93, s96, 3
	s_lshl_b32 s80, s94, 3
	v_writelane_b32 v253, s6, 0
	s_cmpk_lt_i32 s96, 0x100
	v_mov_b32_e32 v196, 0x358637bd
	v_writelane_b32 v253, s7, 1
	s_cselect_b64 s[6:7], -1, 0
	v_writelane_b32 v253, s6, 2
	s_cmpk_lt_i32 s96, 0xb42
	v_mov_b32_e32 v197, 1
	v_writelane_b32 v253, s7, 3
	s_cselect_b64 s[6:7], -1, 0
	v_writelane_b32 v253, s6, 4
	v_mov_b32_e32 v199, 0x1200
	s_movk_i32 s64, 0x6000
	v_writelane_b32 v253, s7, 5
	s_mul_i32 s6, s86, 0x168
	s_or_b32 s6, s6, 2
	s_cmpk_lt_i32 s96, 0x514
	s_mul_i32 s7, s86, 0xa2
	s_cselect_b64 s[8:9], -1, 0
	s_add_i32 s7, s7, 4
	s_lshl_b32 s14, s96, 9
	s_add_u32 s54, s0, 0xb0200
	s_addc_u32 s55, s1, 0
	s_add_u32 s60, s0, 0xb0400
	s_addc_u32 s61, s1, 0
	s_add_u32 s12, s0, 0xb0500
	s_addc_u32 s13, s1, 0
	s_add_u32 s16, s0, 0xb0600
	s_addc_u32 s17, s1, 0
	s_add_u32 s62, s0, 0xb0700
	v_writelane_b32 v253, s8, 6
	s_addc_u32 s63, s1, 0
	s_mov_b32 s33, 0x800000
	v_writelane_b32 v253, s9, 7
	s_add_u32 s8, s0, 0xb0800
	s_addc_u32 s9, s1, 0
	v_writelane_b32 v253, s8, 8
	s_movk_i32 s82, 0x40ff
	s_movk_i32 s26, 0x407f
	v_writelane_b32 v253, s9, 9
	s_add_u32 s8, s0, 0xb0900
	s_addc_u32 s9, s1, 0
	v_writelane_b32 v253, s8, 10
	s_movk_i32 s27, 0xb00
	s_movk_i32 s90, 0x5800
	v_writelane_b32 v253, s9, 11
	s_add_u32 s8, s0, 0xb0a00
	s_addc_u32 s9, s1, 0
	v_writelane_b32 v253, s8, 12
	s_mov_b32 s83, 0
	s_mov_b32 s99, 0
	s_mov_b32 s25, 0
	v_writelane_b32 v253, s9, 13
	s_add_u32 s8, s0, 0xb0b00
	s_addc_u32 s9, s1, 0
	v_writelane_b32 v253, s8, 14
	s_mov_b64 s[28:29], 0x80
	s_mov_b32 s30, 0xbf1b4598
	v_writelane_b32 v253, s9, 15
	s_add_u32 s8, s0, 0xb0c00
	s_addc_u32 s9, s1, 0
	v_writelane_b32 v253, s8, 16
	s_mov_b64 s[34:35], 0x1200
	s_nop 0
	v_writelane_b32 v253, s9, 17
	s_add_u32 s8, s0, 0xb0d00
	s_addc_u32 s9, s1, 0
	v_writelane_b32 v253, s8, 18
	s_nop 1
	v_writelane_b32 v253, s9, 19
	s_add_u32 s8, s0, 0xb0e00
	s_addc_u32 s9, s1, 0
	v_writelane_b32 v253, s8, 20
	s_nop 1
	v_writelane_b32 v253, s9, 21
	s_add_u32 s8, s0, 0xb0f00
	s_addc_u32 s9, s1, 0
	v_writelane_b32 v253, s8, 22
	s_nop 1
	v_writelane_b32 v253, s9, 23
	s_add_u32 s8, s0, 0xb1000
	s_addc_u32 s9, s1, 0
	v_writelane_b32 v253, s8, 24
	s_nop 1
	v_writelane_b32 v253, s9, 25
	s_add_u32 s8, s0, 0xb1100
	s_addc_u32 s9, s1, 0
	v_writelane_b32 v253, s8, 26
	s_nop 1
	v_writelane_b32 v253, s9, 27
	s_add_u32 s8, s0, 0xb1200
	s_addc_u32 s9, s1, 0
	v_writelane_b32 v253, s8, 28
	s_nop 1
	v_writelane_b32 v253, s9, 29
	s_add_u32 s8, s0, 0xb1300
	s_addc_u32 s9, s1, 0
	v_writelane_b32 v253, s8, 30
	s_cmp_eq_u32 s2, 15
	s_nop 0
	v_writelane_b32 v253, s9, 31
	s_cselect_b64 s[8:9], -1, 0
	v_writelane_b32 v253, s8, 32
	s_cmp_eq_u32 s2, 14
	s_nop 0
	v_writelane_b32 v253, s9, 33
	s_cselect_b64 s[8:9], -1, 0
	v_writelane_b32 v253, s8, 34
	s_cmp_eq_u32 s2, 13
	s_nop 0
	v_writelane_b32 v253, s9, 35
	s_cselect_b64 s[8:9], -1, 0
	v_writelane_b32 v253, s8, 36
	s_cmp_eq_u32 s2, 12
	s_nop 0
	v_writelane_b32 v253, s9, 37
	s_cselect_b64 s[8:9], -1, 0
	v_writelane_b32 v253, s8, 38
	s_cmp_eq_u32 s2, 11
	s_nop 0
	v_writelane_b32 v253, s9, 39
	s_cselect_b64 s[8:9], -1, 0
	v_writelane_b32 v253, s8, 40
	s_cmp_eq_u32 s2, 10
	s_nop 0
	v_writelane_b32 v253, s9, 41
	s_cselect_b64 s[8:9], -1, 0
	v_writelane_b32 v253, s8, 42
	s_cmp_eq_u32 s2, 9
	s_nop 0
	v_writelane_b32 v253, s9, 43
	s_cselect_b64 s[8:9], -1, 0
	v_writelane_b32 v253, s8, 44
	s_cmp_eq_u32 s2, 8
	s_nop 0
	v_writelane_b32 v253, s9, 45
	s_cselect_b64 s[8:9], -1, 0
	v_writelane_b32 v253, s8, 46
	s_cmp_eq_u32 s2, 7
	s_nop 0
	v_writelane_b32 v253, s9, 47
	s_cselect_b64 s[8:9], -1, 0
	v_writelane_b32 v253, s8, 48
	s_cmp_eq_u32 s2, 6
	s_nop 0
	v_writelane_b32 v253, s9, 49
	s_cselect_b64 s[8:9], -1, 0
	v_writelane_b32 v253, s8, 50
	s_cmp_eq_u32 s2, 5
	s_nop 0
	v_writelane_b32 v253, s9, 51
	s_cselect_b64 s[8:9], -1, 0
	v_writelane_b32 v253, s8, 52
	s_cmp_eq_u32 s2, 4
	s_nop 0
	v_writelane_b32 v253, s9, 53
	s_cselect_b64 s[8:9], -1, 0
	v_writelane_b32 v253, s8, 54
	s_cmp_eq_u32 s2, 3
	s_nop 0
	v_writelane_b32 v253, s9, 55
	s_cselect_b64 s[8:9], -1, 0
	v_writelane_b32 v253, s8, 56
	s_cmp_eq_u32 s2, 2
	s_nop 0
	v_writelane_b32 v253, s9, 57
	s_cselect_b64 s[8:9], -1, 0
	v_writelane_b32 v253, s8, 58
	s_cmp_eq_u32 s2, 1
	s_nop 0
	v_writelane_b32 v253, s9, 59
	s_cselect_b64 s[8:9], -1, 0
	v_writelane_b32 v253, s8, 60
	s_cmp_eq_u32 s2, 0
	s_nop 0
	v_writelane_b32 v253, s9, 61
	s_cselect_b64 s[8:9], -1, 0
	s_lshl_b32 s2, s2, 8
	s_add_u32 s2, s4, s2
	v_writelane_b32 v253, s8, 62
	s_addc_u32 s4, s5, 0
	s_nop 0
	v_writelane_b32 v253, s9, 63
	s_add_u32 s8, s2, 0x1400
	s_addc_u32 s9, s4, 0
	v_writelane_b32 v254, s8, 0
	s_nop 1
	v_writelane_b32 v254, s9, 1
	s_add_u32 s8, s2, 0x2400
	s_addc_u32 s9, s4, 0
	v_writelane_b32 v254, s8, 2
	s_add_u32 s4, s0, 0xb3400
	s_addc_u32 s5, s1, 0
	v_writelane_b32 v254, s9, 3
	v_writelane_b32 v254, s4, 4
	s_add_u32 s0, s0, 0xb3500
	s_addc_u32 s1, s1, 0
	v_writelane_b32 v254, s5, 5
;     __host__ __device__ bool next(int i, Unit& u) const {
;         const long L = (long)i * G + c; if (L >= nwg) return false;
;         int wgid = (int)L; { const int q = nwg / NXCD, r = nwg % NXCD, xcd = wgid % NXCD, off = wgid / NXCD; wgid = (xcd < r ? xcd * (q + 1) : r * (q + 1) + (xcd - r) * q) + off; }
;         const int nig = WGM * nN, gid = wgid / nig, fm = gid * WGM, gsz = (nM - fm) < WGM ? (nM - fm) : WGM;
;         u.pm = fm + ((wgid % nig) % gsz); u.pn = (wgid % nig) / gsz; return true;
	v_writelane_b32 v254, s0, 6
	s_cmp_lt_i32 s86, 4
	s_nop 0
	v_writelane_b32 v254, s1, 7
	s_mul_i32 s0, s86, 33
	s_cselect_b32 s0, s0, s3
	s_mul_i32 s1, s86, 0xa3
	s_cselect_b32 s1, s1, s7
	s_add_i32 s0, s0, s85
	s_ashr_i32 s2, s0, 31
	s_lshr_b32 s2, s2, 27
	s_add_i32 s2, s0, s2
	s_and_b32 s3, s2, 0xffffffe0
	s_sub_i32 s3, s0, s3
	s_ashr_i32 s0, s2, 5
	s_lshl_b32 s2, s0, 3
	s_sub_i32 s0, 0x41, s2
	s_min_u32 s4, s0, 8
	s_cmp_lt_i32 s86, 2
	s_mul_i32 s0, s86, 0x169
	s_cselect_b32 s0, s0, s6
	s_add_i32 s0, s0, s85
	s_mul_hi_i32 s5, s0, 0x2e8ba2e9
	s_lshr_b32 s6, s5, 31
	s_ashr_i32 s5, s5, 5
	s_add_i32 s5, s5, s6
	v_cvt_f32_ubyte0_e32 v1, s4
	s_mul_i32 s6, s5, 0xb0
	s_add_i32 s1, s1, s85
	v_cvt_f32_i32_e32 v0, s3
	v_rcp_iflag_f32_e32 v2, v1
	s_sub_i32 s6, s0, s6
	s_mul_hi_i32 s0, s1, 0x66666667
	s_lshr_b32 s7, s0, 31
	s_ashr_i32 s0, s0, 6
	s_add_i32 s0, s0, s7
	s_lshl_b32 s9, s0, 3
	v_mul_f32_e32 v2, v0, v2
	s_mul_i32 s7, s0, 0xa0
	s_lshl_b32 s5, s5, 3
	s_sub_i32 s0, 0x41, s9
	v_trunc_f32_e32 v2, v2
	s_sub_i32 s7, s1, s7
	s_sub_i32 s1, 0x83, s5
	s_min_u32 s10, s0, 8
	s_ashr_i32 s0, s3, 30
	v_fma_f32 v0, -v2, v1, v0
	s_min_u32 s8, s1, 8
	s_or_b32 s11, s0, 1
	v_cmp_ge_f32_e64 s[0:1], |v0|, v1
	v_cvt_i32_f32_e32 v0, v2
	s_and_b64 s[0:1], s[0:1], exec
	s_cselect_b32 s0, s11, 0
	v_cvt_f32_ubyte0_e32 v1, s8
	v_readfirstlane_b32 s1, v0
	s_add_i32 s0, s1, s0
	s_mul_i32 s1, s0, s4
	v_cvt_f32_i32_e32 v0, s6
	v_rcp_iflag_f32_e32 v2, v1
	s_sub_i32 s1, s3, s1
	s_sext_i32_i8 s1, s1
	s_add_i32 s1, s2, s1
	s_sext_i32_i8 s3, s0
	s_ashr_i32 s0, s6, 30
	s_or_b32 s2, s0, 1
	v_mul_f32_e32 v2, v0, v2
	v_writelane_b32 v254, s1, 8
	s_ashr_i32 s0, s1, 31
	v_trunc_f32_e32 v2, v2
	v_writelane_b32 v254, s0, 9
	v_fma_f32 v0, -v2, v1, v0
	v_writelane_b32 v254, s3, 10
	s_ashr_i32 s0, s3, 31
	v_writelane_b32 v254, s0, 11
	v_cmp_ge_f32_e64 s[0:1], |v0|, v1
	v_cvt_i32_f32_e32 v0, v2
	s_and_b64 s[0:1], s[0:1], exec
	v_cvt_f32_ubyte0_e32 v1, s10
	s_cselect_b32 s0, s2, 0
	v_readfirstlane_b32 s1, v0
	v_cvt_f32_i32_e32 v0, s7
	v_rcp_iflag_f32_e32 v2, v1
	s_add_i32 s2, s1, s0
	s_mul_i32 s0, s2, s8
	s_sub_i32 s0, s6, s0
	s_sext_i32_i16 s0, s0
	v_mul_f32_e32 v2, v0, v2
	s_add_i32 s0, s5, s0
	v_trunc_f32_e32 v2, v2
	v_writelane_b32 v254, s0, 12
	s_ashr_i32 s0, s7, 30
	v_fma_f32 v0, -v2, v1, v0
	s_or_b32 s3, s0, 1
	v_cmp_ge_f32_e64 s[0:1], |v0|, v1
	s_and_b64 s[0:1], s[0:1], exec
	s_load_dword s1, s[78:79], 0x118
	v_cvt_i32_f32_e32 v0, v2
	s_mul_i32 s0, s95, s94
	s_mov_b32 s95, s14
	v_mov_b32_e32 v1, 0
	s_waitcnt lgkmcnt(0)
	s_mul_i32 s91, s0, s1
	s_cselect_b32 s0, s3, 0
	v_readfirstlane_b32 s1, v0
	s_add_i32 s0, s1, s0
	s_mul_i32 s1, s0, s10
	s_sub_i32 s1, s7, s1
	s_sext_i32_i16 s1, s1
	s_add_i32 s1, s9, s1
	v_writelane_b32 v254, s1, 13
	s_sext_i32_i16 s1, s2
	v_writelane_b32 v254, s1, 14
	s_sext_i32_i16 s0, s0
	v_writelane_b32 v254, s0, 15
	s_lshl_b32 s0, s96, 4
	v_writelane_b32 v254, s0, 16
	s_lshl_b32 s0, s96, 8
	v_writelane_b32 v254, s0, 17
	s_add_i32 s0, s93, 0xffffcc80
	v_writelane_b32 v254, s0, 18
	s_add_i32 s0, s93, 0xffffcd00
	v_writelane_b32 v254, s0, 19
	s_add_i32 s0, s93, 0xffffd300
	v_writelane_b32 v254, s0, 20
	s_add_i32 s0, s93, 0xffff7ec0
	v_writelane_b32 v254, s0, 21
	s_add_i32 s0, 0, 0x1c400
	v_writelane_b32 v254, s0, 22
	s_add_i32 s0, 0, 0x1d000
	v_writelane_b32 v254, s0, 23
	s_add_i32 s0, 0, 0x1ce00
	v_writelane_b32 v254, s0, 24
	s_add_i32 s0, 0, 0x1cc00
	v_writelane_b32 v254, s0, 25
	s_add_i32 s0, 0, 0x21d00
	v_writelane_b32 v254, s0, 26
	s_add_i32 s0, 0, 0x16800
	v_writelane_b32 v254, s0, 27
	s_add_i32 s0, 0, 0x14400
	v_writelane_b32 v254, s0, 28
	s_add_i32 s0, 0, 0x18c00
	v_writelane_b32 v254, s0, 29
	s_add_i32 s0, 0, 0x1b000
	v_writelane_b32 v254, s0, 30
	s_add_i32 s0, 0, 0x1d400
	v_writelane_b32 v254, s0, 31
	s_add_i32 s0, 0, 0x1f800
	v_writelane_b32 v254, s0, 32
	s_add_i32 s0, 0, 0x1a800
	v_writelane_b32 v254, s0, 33
	s_add_i32 s0, 0, 0x21c00
	v_writelane_b32 v254, s0, 34
	s_add_i32 s0, 0, 0x20800
	v_writelane_b32 v254, s0, 35
	s_add_i32 s0, 0, 0x20000
	v_writelane_b32 v254, s0, 36
	s_add_i32 s0, 0, 0x13c00
	v_writelane_b32 v254, s0, 37
	s_add_i32 s0, 0, 0x23ff0
	s_ashr_i32 s81, s80, 31
	v_writelane_b32 v254, s0, 38
	s_add_i32 s0, 0, 0x23ff4
	v_writelane_b32 v254, s0, 39
	s_lshl_b64 s[0:1], s[80:81], 6
	v_writelane_b32 v254, s0, 40
	v_writelane_b32 v255, s91, 0
	v_writelane_b32 v255, s12, 1
	v_writelane_b32 v254, s1, 41
	s_lshl_b64 s[0:1], s[80:81], 11
	v_writelane_b32 v254, s0, 42
	v_writelane_b32 v255, s13, 2
	v_mbcnt_lo_u32_b32 v0, -1, 0
	v_writelane_b32 v254, s1, 43
	s_lshl_b64 s[0:1], s[80:81], 12
	v_writelane_b32 v254, s0, 44
	v_writelane_b32 v255, s16, 3
	v_mbcnt_hi_u32_b32 v198, -1, v0
	v_writelane_b32 v254, s1, 45
	v_writelane_b32 v254, s78, 46
	s_mov_b32 s0, s94
	s_movk_i32 s3, 0x400
	v_writelane_b32 v254, s79, 47
	v_writelane_b32 v254, s0, 48
	s_movk_i32 s14, 0x203f
	v_writelane_b32 v255, s17, 4
	v_writelane_b32 v254, s1, 49
	v_writelane_b32 v254, s84, 50
	v_writelane_b32 v254, s85, 51
	v_writelane_b32 v254, s86, 52
	v_writelane_b32 v254, s87, 53
	v_writelane_b32 v254, s93, 54
	v_writelane_b32 v254, s80, 55
	s_barrier
	s_nop 0
	v_writelane_b32 v254, s81, 56
	v_writelane_b32 v254, s95, 57
	v_writelane_b32 v254, s54, 58
	s_nop 1
	v_writelane_b32 v254, s55, 59
	v_writelane_b32 v254, s60, 60
	s_nop 1
	v_writelane_b32 v254, s61, 61
	v_writelane_b32 v254, s62, 62
	s_nop 1
	v_writelane_b32 v254, s63, 63
	s_branch .LBB0_19

; #define PG8_STAGE(bufoff, gbase, voff) do { _Pragma("unroll") for (int _i = 0; _i < 2; ++_i) \
;         __builtin_amdgcn_global_load_lds((const unsigned*)((const char*)(gbase) + (voff)[_i]), (PG8_LAS unsigned*)(lds + (bufoff) + ldsw + _i * 8192), 16, 0, 0); } while (0)
; #define PG8_WAIT_V(n) asm volatile("s_waitcnt vmcnt(" #n ")" ::: "memory")
; #define PG8_BAR __builtin_amdgcn_s_barrier()
;     __host__ __device__ bool next(int i, Unit& u) const {
;         const long L = (long)i * G + c; if (L >= nwg) return false;
;         int wgid = (int)L; { const int q = nwg / NXCD, r = nwg % NXCD, xcd = wgid % NXCD, off = wgid / NXCD; wgid = (xcd < r ? xcd * (q + 1) : r * (q + 1) + (xcd - r) * q) + off; }
;         const int nig = WGM * nN, gid = wgid / nig, fm = gid * WGM, gsz = (nM - fm) < WGM ? (nM - fm) : WGM;
;         u.pm = fm + ((wgid % nig) % gsz); u.pn = (wgid % nig) / gsz; return true;
; template <class Epi, class Sched, bool ALIGN_EPI = false, bool SP2 = false>
; __device__ __forceinline__ void gemm_phase(PG8_LAS unsigned char* lds, const Gemm g, const Sched& S, const Epi& E, int tid_in) {
;     ...
;     const char* cA = (const char*)g.A + (size_t)cur.pm * tstepA + a_unit_off(g, cur.pn); const char* cB = (const char*)g.Bt + (size_t)cur.pn * tstepB;
;     S.a_ready(cur);
;     if constexpr (SP2) {
;         PG8_STAGE(PG8_SB(0, 0), cB, voffB); PG8_STAGE(PG8_SB(0, 1), cB + hstep, voffB); PG8_STAGE(PG8_SA(0, 0), cA, voffA); PG8_STAGE(PG8_SA(0, 1), cA + hstepA, voffA);
;         if (wr == 1) PG8_BAR;
;         PG8_WAIT_V(2); PG8_BAR;
;         PG8_STAGE(PG8_SB(1, 0), cB + kstep, voffB); PG8_STAGE(PG8_SA(1, 0), cA + kstep, voffA); PG8_STAGE(PG8_SB(1, 1), cB + hstep + kstep, voffB);
;         PG8_WAIT_V(6); PG8_BAR;
;     } else {
;         PG8_STAGE(PG8_SB(0, 0), cB, voffB); PG8_STAGE(PG8_SA(0, 0), cA, voffA); PG8_STAGE(PG8_SB(0, 1), cB + hstep, voffB); PG8_STAGE(PG8_SA(0, 1), cA + hstepA, voffA);
;         if (wr == 1) PG8_BAR;
;         PG8_WAIT_V(4); PG8_BAR;
;         PG8_STAGE(PG8_SB(1, 0), cB + kstep, voffB); PG8_STAGE(PG8_SA(1, 0), cA + kstep, voffA); PG8_STAGE(PG8_SB(1, 1), cB + hstep + kstep, voffB);
;         PG8_WAIT_V(6); PG8_BAR;
.LBB0_389:
	s_and_b64 vcc, exec, s[0:1]
	s_cbranch_vccz .LBB0_498
	s_cmp_gt_i32 s65, 2
	s_cbranch_scc0 .LBB0_494
	s_cmp_gt_i32 s65, 4
	s_mov_b64 s[0:1], -1
	s_cbranch_scc0 .LBB0_495
	s_cmp_lt_i32 s65, 6
	s_mov_b64 s[70:71], -1
	s_cbranch_scc0 .LBB0_506
	v_readlane_b32 s8, v253, 4
	v_readlane_b32 s9, v253, 5
	s_movk_i32 s0, 0x400
	s_andn2_b64 vcc, exec, s[8:9]
	v_cndmask_b32_e64 v0, 0, 1, s[8:9]
	v_cmp_ne_u32_e64 s[36:37], 1, v0
	v_readfirstlane_b32 s13, v202
	s_cbranch_vccnz .LBB0_395
	v_readlane_b32 s23, v254, 14
	v_readlane_b32 s2, v254, 12
	s_movk_i32 s98, 0xb42
	s_cmp_lg_u32 s94, 0x100
	s_cbranch_scc1 .Lpre_done
	s_cmp_eq_u32 s99, 1
	s_cbranch_scc0 .Lpre_real
	s_movk_i32 s98, 0x100
	s_branch .Lpre_done
.Lpre_real:
	s_movk_i32 s98, 0xb00
	s_and_b32 s100, s96, 7
	s_cmp_gt_u32 s100, 2
	s_cbranch_scc1 .Lpre_done
	s_lshr_b32 s101, s96, 3
	s_add_i32 s101, s101, -1
	s_cmp_gt_u32 s101, 21
	s_cbranch_scc1 .Lpre_done
	s_mul_i32 s101, s101, 3
	s_add_i32 s101, s101, s100
	s_and_b32 s100, s101, 7
	s_lshr_b32 s101, s101, 3
	s_addk_i32 s101, 0x160
	s_mul_i32 s2, s100, 0x168
	s_min_u32 s100, s100, 2
	s_add_i32 s2, s2, s100
	s_add_i32 s2, s2, s101
	s_mul_hi_u32 s23, s2, 0x2e8ba2e9
	s_lshr_b32 s23, s23, 5
	s_mul_i32 s100, s23, 0xb0
	s_sub_i32 s100, s2, s100
	s_lshl_b32 s23, s23, 3
	s_cmp_eq_u32 s23, 0x80
	s_cbranch_scc1 .Lpre_g16
	s_and_b32 s2, s100, 7
	s_add_i32 s2, s2, s23
	s_lshr_b32 s23, s100, 3
	s_branch .Lpre_done
.Lpre_g16:
	s_mul_i32 s101, s100, 0x5556
	s_lshr_b32 s101, s101, 16
	s_mul_i32 s2, s101, 3
	s_sub_i32 s2, s100, s2
	s_add_i32 s2, s2, s23
	s_mov_b32 s23, s101
.Lpre_done:
.LBB0_395:
	s_and_b64 vcc, exec, s[36:37]
	s_cbranch_vccnz .LBB0_505
	v_bfe_i32 v3, v202, 27, 1
	v_lshlrev_b32_e32 v2, 4, v202
	v_lshrrev_b32_e32 v3, 22, v3
	v_add_u32_e32 v3, v2, v3
	v_and_b32_e32 v3, 0xfffffc00, v3
	v_sub_u32_e32 v3, v2, v3
	v_ashrrev_i32_e32 v0, 31, v202
	v_lshrrev_b32_e32 v4, 4, v3
	v_lshrrev_b32_e32 v0, 26, v0
	v_bitop3_b32 v3, v4, v3, 32 bitop3:0x6c
	v_add_u32_e32 v0, v202, v0
	v_ashrrev_i32_e32 v5, 31, v3
	v_ashrrev_i32_e32 v0, 6, v0
	v_lshrrev_b32_e32 v5, 26, v5
	v_lshlrev_b32_e32 v4, 3, v0
	v_add_u32_e32 v5, v3, v5
	s_cmp_eq_u32 s40, 0
	s_mov_b32 s1, 0x4d00000
	v_and_b32_e32 v4, -16, v4
	v_ashrrev_i32_e32 v6, 6, v5
	v_lshlrev_b32_e32 v0, 5, v0
	s_cselect_b32 s1, s1, 0x6f00000
	v_add_u32_e32 v4, v6, v4
	v_and_b32_e32 v14, 32, v0
	v_and_b32_e32 v0, 0xc0, v5
	s_add_u32 s24, s4, s1
	v_sub_u32_e32 v0, v3, v0
	v_lshlrev_b32_e32 v3, 1, v4
	v_lshrrev_b32_e32 v5, 2, v4
	v_and_b32_e32 v6, 3, v6
	s_mov_b32 s1, 0x7fffffe0
	v_ashrrev_i16_sdwa v0, v197, sext(v0) dst_sel:DWORD dst_unused:UNUSED_PAD src0_sel:DWORD src1_sel:BYTE_0
	v_and_b32_e32 v3, 24, v3
	v_and_b32_e32 v5, 4, v5
	v_and_or_b32 v6, v4, s1, v6
	v_bfe_i32 v15, v0, 0, 16
	v_or3_b32 v3, v6, v5, v3
	v_add_u32_e32 v0, v14, v15
	v_mul_lo_u32 v16, s0, v4
	v_mul_lo_u32 v3, s0, v3
	v_add_u32_e32 v2, 0x2000, v2
	v_add_lshl_u32 v148, v16, v0, 1
	v_add_lshl_u32 v0, v3, v0, 1
	v_ashrrev_i32_e32 v3, 31, v2
	v_lshrrev_b32_e32 v3, 22, v3
	v_add_u32_e32 v3, v2, v3
	v_ashrrev_i32_e32 v3, 10, v3
	v_mul_i32_i24_e32 v4, 0x400, v3
	v_sub_u32_e32 v2, v2, v4
	v_lshrrev_b32_e32 v4, 4, v2
	v_bitop3_b32 v2, v4, v2, 32 bitop3:0x6c
	v_ashrrev_i32_e32 v5, 31, v2
	v_lshrrev_b32_e32 v5, 26, v5
	v_lshlrev_b32_e32 v4, 3, v3
	v_add_u32_e32 v5, v2, v5
	s_addc_u32 s36, s5, 0
	v_and_b32_e32 v4, -16, v4
	v_ashrrev_i32_e32 v6, 6, v5
	s_mul_i32 s11, s0, 0x1fc
	s_ashr_i32 s8, s2, 31
	v_add_u32_e32 v4, v6, v4
	v_and_b32_e32 v6, 3, v6
	s_mul_hi_i32 s10, s0, 0x1fc
	s_mul_i32 s8, s11, s8
	s_mul_hi_u32 s9, s11, s2
	v_and_or_b32 v6, v4, s1, v6
	s_ashr_i32 s1, s0, 31
	s_add_i32 s8, s9, s8
	s_mul_i32 s9, s10, s2
	s_lshl_b64 s[20:21], s[0:1], 9
	v_writelane_b32 v255, s10, 10
	s_add_i32 s10, s8, s9
	s_ashr_i32 s8, s23, 31
	s_mul_i32 s8, s20, s8
	s_mul_hi_u32 s9, s20, s23
	s_add_i32 s22, s9, s8
	s_lshr_b64 s[8:9], s[0:1], 23
	v_lshlrev_b32_e32 v3, 5, v3
	s_ashr_i32 s15, s13, 6
	s_mul_i32 s8, s8, s23
	s_ashr_i32 s12, s13, 8
	v_and_b32_e32 v17, 32, v3
	v_and_b32_e32 v3, 0xc0, v5
	s_lshl_b64 s[18:19], s[0:1], 8
	s_lshl_b32 s91, s15, 10
	s_add_i32 s22, s22, s8
	s_mul_i32 s8, s20, s23
	v_sub_u32_e32 v2, v2, v3
	v_lshlrev_b32_e32 v3, 1, v4
	v_lshrrev_b32_e32 v5, 2, v4
	s_add_u32 s60, s24, s8
	v_ashrrev_i16_sdwa v2, v197, sext(v2) dst_sel:DWORD dst_unused:UNUSED_PAD src0_sel:DWORD src1_sel:BYTE_0
	v_and_b32_e32 v3, 24, v3
	v_and_b32_e32 v5, 4, v5
	s_addc_u32 s61, s36, s22
	s_add_i32 s78, s91, 0
	v_bfe_i32 v18, v2, 0, 16
	v_or3_b32 v3, v6, v5, v3
	v_writelane_b32 v255, s11, 12
	s_add_i32 m0, s78, 0x10000
	v_add_u32_e32 v2, v17, v18
	v_mul_lo_u32 v3, s0, v3
	v_writelane_b32 v255, s24, 14
	global_load_lds_dwordx4 v0, s[60:61]
	s_add_i32 m0, s78, 0x12000
	v_add_lshl_u32 v152, v3, v2, 1
	v_writelane_b32 v255, s36, 15
	s_add_u32 s36, s60, s18
	global_load_lds_dwordx4 v152, s[60:61]
	s_addc_u32 s37, s61, s19
	s_add_i32 m0, s78, 0x14000
	s_mul_i32 s11, s11, s2
	global_load_lds_dwordx4 v0, s[36:37]
	s_add_i32 m0, s78, 0x16000
	s_add_u32 s62, s4, s11
	s_addc_u32 s63, s5, s10
	s_add_i32 s79, s78, 0x2000
	v_mul_lo_u32 v19, s0, v4
	global_load_lds_dwordx4 v152, s[36:37]
	s_mov_b32 m0, s78
	s_add_u32 s8, s62, s18
	v_add_lshl_u32 v150, v19, v2, 1
	global_load_lds_dwordx4 v148, s[62:63]
	s_mov_b32 m0, s79
	s_addc_u32 s9, s63, s19
	s_add_i32 s80, s78, 0x4000
	global_load_lds_dwordx4 v150, s[62:63]
	s_mov_b32 m0, s80
	s_add_i32 s81, s78, 0x6000
	global_load_lds_dwordx4 v148, s[8:9]
	s_mov_b32 m0, s81
	v_readlane_b32 s38, v255, 5
	global_load_lds_dwordx4 v150, s[8:9]
	v_readlane_b32 s39, v255, 6
	s_load_dwordx4 s[8:11], s[38:39], 0xe8
	v_mov_b32_e32 v153, v1
	s_cmp_eq_u32 s12, 1
	v_lshl_add_u64 v[4:5], s[36:37], 0, v[0:1]
	v_lshl_add_u64 v[2:3], s[36:37], 0, v[152:153]
	s_cselect_b64 s[36:37], -1, 0
	v_mov_b32_e32 v149, v1
	v_mov_b32_e32 v151, v1
	v_writelane_b32 v255, s36, 16
	v_lshl_add_u64 v[10:11], s[60:61], 0, v[0:1]
	v_lshl_add_u64 v[6:7], s[60:61], 0, v[152:153]
	v_lshl_add_u64 v[8:9], s[62:63], 0, v[148:149]
	v_writelane_b32 v255, s37, 17
	s_cmp_lg_u32 s12, 1
	v_lshl_add_u64 v[12:13], s[62:63], 0, v[150:151]
	s_cbranch_scc1 .LBB0_398
	s_barrier

;     __host__ __device__ bool next(int i, Unit& u) const {
;         const long L = (long)i * G + c; if (L >= nwg) return false;
; template <class Epi, class Sched, bool ALIGN_EPI = false, bool SP2 = false>
; __device__ __forceinline__ void gemm_phase(PG8_LAS unsigned char* lds, const Gemm g, const Sched& S, const Epi& E, int tid_in) {
;     ...
;         const bool has_next = S.next(ui + 1, nxt);
.LBB0_401:
	s_add_i32 s22, s22, 1
	v_readlane_b32 s0, v254, 53
	s_mul_i32 s0, s22, s0
	s_mul_hi_u32 s1, s22, s94
	s_add_i32 s1, s1, s0
	s_mul_i32 s0, s22, s94
	s_add_u32 s0, s0, s96
	s_addc_u32 s1, s1, s97
	v_mov_b32_e32 v2, s98
	v_mov_b32_e32 v3, 0
	v_cmp_lt_i64_e64 s[58:59], s[0:1], v[2:3]
	v_cmp_ge_i64_e32 vcc, s[0:1], v[2:3]
	s_cbranch_vccnz .LBB0_407
	s_ashr_i32 s1, s0, 31
	s_lshr_b32 s1, s1, 29
	s_add_i32 s8, s0, s1
	s_and_b32 s1, s8, -8
	s_sub_i32 s9, s0, s1
	s_cmp_gt_i32 s9, 1
	s_mov_b64 s[0:1], -1
	s_cbranch_scc0 .LBB0_404
	s_mul_i32 s0, s9, 0x168
	s_or_b32 s12, s0, 2
	s_mov_b64 s[0:1], 0

; __global__ void __launch_bounds__(512, 2) fwd_mega(Args a_) {
;     ...
;         int kind = 15, slab = 0;
;         if (ph == 0) kind = 0;
;         else if (ph <= 10) { const int q = (ph - 1) % 5; slab = (ph - 1) / 5; kind = q == 0 ? 1 : (q == 1 ? 14 : (q == 2 ? 2 : (q == 3 ? 3 : 4))); }
;         else if (ph == 11) kind = 5; else if (ph == 12) kind = 6;
;         else if (ph <= 26) { kind = 7 + (ph - 13) % 7; slab = (ph - 13) / 7; }
;         else if (ph == 27) { kind = 5; slab = 1; } else if (ph == 28) { kind = 6; slab = 1; }
;     ...
;         default: if (PHM & 2048) final_norm((const bf16*)(ws + WS_HBNEW), (const float*)(ws + WS_PB), ap->in[5], ap->out, tid); break;
;         }
;         if (phc < 29) { unsigned z2 = 0u; asm volatile("" : "+v"(z2)); const int t2 = wave_s * 64 + (int)__builtin_amdgcn_mbcnt_hi(~0u, __builtin_amdgcn_mbcnt_lo(~0u, z2)); xcd_barrier(xbar, t2); }
.LBB0_961:
	s_cmp_eq_u32 s99, 1
	s_cbranch_scc1 .Lpre_back
	s_cmp_lg_u32 s94, 0x100
	s_cbranch_scc1 .Lpre_none
	s_cmp_eq_u32 s83, 10
	s_cselect_b32 s100, 0, 1
	s_cbranch_scc1 .Lpre_chk
	s_cmp_eq_u32 s83, 26
	s_cbranch_scc0 .Lpre_none
.Lpre_chk:
	s_and_b32 s101, s96, 7
	s_cmp_gt_u32 s101, 2
	s_cbranch_scc1 .Lpre_none
	s_lshr_b32 s101, s96, 3
	s_add_i32 s101, s101, -1
	s_cmp_gt_u32 s101, 21
	s_cbranch_scc1 .Lpre_none
	s_mov_b32 s99, 1
	s_mov_b32 s65, 5
	s_mov_b32 s40, s100
	s_branch .Ltramp_b50
.Lpre_back:
	s_mov_b32 s99, 0
